# final RMSNorm phase: output stores back to the default cache policy (non-temporal kept on its loads)
# speedup vs baseline: 1.0307x; 1.0046x over previous
.LBB0_1664:
	v_ashrrev_i32_e32 v1, 31, v0
	v_lshlrev_b64 v[16:17], 11, v[0:1]
	v_lshl_add_u64 v[20:21], v[2:3], 0, v[16:17]
	global_load_dwordx2 v[22:23], v[20:21], off nt
	global_load_dwordx2 v[24:25], v[20:21], off offset:512 nt
	global_load_dwordx2 v[26:27], v[20:21], off offset:1024 nt
	global_load_dwordx2 v[28:29], v[20:21], off offset:1536 nt
	global_load_dwordx4 v[16:19], v[6:7], off
	s_waitcnt vmcnt(4)
	v_and_b32_e32 v21, 0xffff0000, v22
	s_waitcnt vmcnt(3)
	v_and_b32_e32 v31, 0xffff0000, v24
	v_lshlrev_b32_e32 v20, 16, v22
	v_lshlrev_b32_e32 v30, 16, v24
	s_waitcnt vmcnt(2)
	v_and_b32_e32 v33, 0xffff0000, v26
	s_waitcnt vmcnt(1)
	v_and_b32_e32 v35, 0xffff0000, v28
	v_mov_b32_e32 v38, v21
	v_mov_b32_e32 v39, v31
	v_lshlrev_b32_e32 v22, 16, v23
	v_lshlrev_b32_e32 v24, 16, v25
	v_lshlrev_b32_e32 v32, 16, v26
	v_lshlrev_b32_e32 v34, 16, v28
	v_mov_b32_e32 v36, v20
	v_mov_b32_e32 v37, v30
	v_mov_b32_e32 v46, v33
	v_mov_b32_e32 v47, v35
	v_pk_mul_f32 v[38:39], v[38:39], v[38:39]
	v_and_b32_e32 v23, 0xffff0000, v23
	v_and_b32_e32 v25, 0xffff0000, v25
	v_lshlrev_b32_e32 v26, 16, v27
	v_lshlrev_b32_e32 v28, 16, v29
	v_mov_b32_e32 v40, v22
	v_mov_b32_e32 v41, v24
	v_mov_b32_e32 v44, v32
	v_mov_b32_e32 v45, v34
	v_pk_mul_f32 v[46:47], v[46:47], v[46:47]
	v_pk_fma_f32 v[36:37], v[36:37], v[36:37], v[38:39]
	v_and_b32_e32 v27, 0xffff0000, v27
	v_and_b32_e32 v29, 0xffff0000, v29
	v_mov_b32_e32 v42, v23
	v_mov_b32_e32 v43, v25
	v_mov_b32_e32 v48, v26
	v_mov_b32_e32 v49, v28
	v_pk_fma_f32 v[38:39], v[44:45], v[44:45], v[46:47]
	v_pk_fma_f32 v[36:37], v[40:41], v[40:41], v[36:37]
	v_mov_b32_e32 v50, v27
	v_mov_b32_e32 v51, v29
	v_pk_fma_f32 v[38:39], v[48:49], v[48:49], v[38:39]
	v_pk_fma_f32 v[36:37], v[42:43], v[42:43], v[36:37]
	v_pk_fma_f32 v[38:39], v[50:51], v[50:51], v[38:39]
	v_add_f32_e32 v15, v36, v37
	v_add_f32_e32 v15, v15, v38
	v_add_f32_e32 v15, v15, v39
	ds_bpermute_b32 v36, v8, v15
	s_waitcnt lgkmcnt(0)
	v_add_f32_e32 v15, v15, v36
	ds_bpermute_b32 v36, v9, v15
	s_waitcnt lgkmcnt(0)
	v_add_f32_e32 v15, v15, v36
	ds_bpermute_b32 v36, v10, v15
	s_waitcnt lgkmcnt(0)
	v_add_f32_e32 v15, v15, v36
	ds_bpermute_b32 v36, v11, v15
	s_waitcnt lgkmcnt(0)
	v_add_f32_e32 v15, v15, v36
	ds_bpermute_b32 v36, v12, v15
	s_waitcnt lgkmcnt(0)
	v_add_f32_e32 v15, v15, v36
	ds_bpermute_b32 v36, v13, v15
	s_waitcnt lgkmcnt(0)
	v_add_f32_e32 v15, v15, v36
	v_fmamk_f32 v15, v15, 0x3a800000, v14
	v_mul_f32_e32 v36, 0x4b800000, v15
	v_cmp_gt_f32_e32 vcc, s2, v15
	s_nop 1
	v_cndmask_b32_e32 v15, v15, v36, vcc
	v_rsq_f32_e32 v15, v15
	v_lshlrev_b64 v[36:37], 12, v[0:1]
	v_lshl_add_u64 v[36:37], v[4:5], 0, v[36:37]
	v_add_u32_e32 v0, s44, v0
	v_mul_f32_e32 v1, 0x45800000, v15
	v_cndmask_b32_e32 v38, v15, v1, vcc
	v_pk_mul_f32 v[20:21], v[38:39], v[20:21] op_sel_hi:[0,1]
	v_pk_mul_f32 v[22:23], v[38:39], v[22:23] op_sel_hi:[0,1]
	s_waitcnt vmcnt(0)
	v_pk_mul_f32 v[16:17], v[16:17], v[20:21]
	v_pk_mul_f32 v[18:19], v[18:19], v[22:23]
	global_store_dwordx4 v[36:37], v[16:19], off
	global_load_dwordx4 v[16:19], v[6:7], off offset:1024
	v_pk_mul_f32 v[20:21], v[38:39], v[30:31] op_sel_hi:[0,1]
	v_pk_mul_f32 v[22:23], v[38:39], v[24:25] op_sel_hi:[0,1]
	v_cmp_lt_i32_e32 vcc, s3, v0
	s_or_b64 s[0:1], vcc, s[0:1]
	s_waitcnt vmcnt(0)
	v_pk_mul_f32 v[16:17], v[16:17], v[20:21]
	v_pk_mul_f32 v[18:19], v[18:19], v[22:23]
	global_store_dwordx4 v[36:37], v[16:19], off offset:1024
	global_load_dwordx4 v[16:19], v[6:7], off offset:2048
	v_pk_mul_f32 v[20:21], v[38:39], v[32:33] op_sel_hi:[0,1]
	v_pk_mul_f32 v[22:23], v[38:39], v[26:27] op_sel_hi:[0,1]
	s_waitcnt vmcnt(0)
	v_pk_mul_f32 v[16:17], v[16:17], v[20:21]
	v_pk_mul_f32 v[18:19], v[18:19], v[22:23]
	global_store_dwordx4 v[36:37], v[16:19], off offset:2048
	global_load_dwordx4 v[16:19], v[6:7], off offset:3072
	v_pk_mul_f32 v[20:21], v[38:39], v[34:35] op_sel_hi:[0,1]
	v_pk_mul_f32 v[22:23], v[38:39], v[28:29] op_sel_hi:[0,1]
	s_waitcnt vmcnt(0)
	v_pk_mul_f32 v[16:17], v[16:17], v[20:21]
	v_pk_mul_f32 v[18:19], v[18:19], v[22:23]
	global_store_dwordx4 v[36:37], v[16:19], off offset:3072
	s_andn2_b64 exec, exec, s[0:1]
	s_cbranch_execnz .LBB0_1664
